# EpiGU (P3 rest): all 8 rstd loads in one batch, issued before the ALIGN_EPI barrier
# speedup vs baseline: 1.0129x; 1.0129x over previous
.LBB0_1238:
	s_add_u32 s28, s26, 0xfffc0080
	s_addc_u32 s29, s27, -1
	s_add_i32 s52, 0, 0x10000
	s_cmp_eq_u32 s51, 12
	s_cselect_b32 s31, s15, s29
	s_cselect_b32 s30, s23, s28
	v_add_u32_e32 v140, s52, v141
	s_cselect_b32 s29, s13, s50
	s_cselect_b32 s28, s48, s49
	s_add_i32 s54, 0, 0x14000
	ds_read_b128 v[144:147], v140
	ds_read_b128 v[148:151], v140 offset:1024
	ds_read_b128 v[152:155], v140 offset:2048
	ds_read_b128 v[156:159], v140 offset:3072
	v_add_u32_e32 v140, s54, v141
	ds_read_b128 v[160:163], v140
	ds_read_b128 v[164:167], v140 offset:1024
	ds_read_b128 v[168:171], v140 offset:2048
	ds_read_b128 v[172:175], v140 offset:3072
	v_lshl_add_u64 v[210:211], s[26:27], 0, v[136:137]
	s_add_i32 m0, s25, 0xc000
	ds_read_b128 v[176:179], v143
	ds_read_b128 v[180:183], v143 offset:1024
	ds_read_b128 v[184:187], v143 offset:2048
	ds_read_b128 v[188:191], v143 offset:3072
	ds_read_b128 v[192:195], v143 offset:4096
	ds_read_b128 v[196:199], v143 offset:5120
	ds_read_b128 v[200:203], v143 offset:6144
	ds_read_b128 v[204:207], v143 offset:7168
	global_load_lds_dwordx4 v[210:211], off
	v_lshl_add_u64 v[210:211], s[26:27], 0, v[138:139]
	s_add_i32 m0, s25, 0xe000
	s_nop 0
	global_load_lds_dwordx4 v[210:211], off
	s_waitcnt vmcnt(8)
	s_waitcnt lgkmcnt(0)
	s_barrier
	s_setprio 1
	s_waitcnt lgkmcnt(0)
	v_mfma_f32_16x16x32_bf16 v[126:129], v[144:147], v[176:179], v[126:129]
	v_mfma_f32_16x16x32_bf16 v[118:121], v[152:155], v[176:179], v[118:121]
	v_mfma_f32_16x16x32_bf16 v[110:113], v[144:147], v[184:187], v[110:113]
	v_mfma_f32_16x16x32_bf16 v[102:105], v[152:155], v[184:187], v[102:105]
	v_mfma_f32_16x16x32_bf16 v[94:97], v[144:147], v[192:195], v[94:97]
	v_mfma_f32_16x16x32_bf16 v[86:89], v[152:155], v[192:195], v[86:89]
	v_mfma_f32_16x16x32_bf16 v[78:81], v[144:147], v[200:203], v[78:81]
	v_mfma_f32_16x16x32_bf16 v[70:73], v[152:155], v[200:203], v[70:73]
	v_mfma_f32_16x16x32_bf16 v[126:129], v[148:151], v[180:183], v[126:129]
	v_mfma_f32_16x16x32_bf16 v[118:121], v[156:159], v[180:183], v[118:121]
	v_mfma_f32_16x16x32_bf16 v[110:113], v[148:151], v[188:191], v[110:113]
	v_mfma_f32_16x16x32_bf16 v[102:105], v[156:159], v[188:191], v[102:105]
	v_mfma_f32_16x16x32_bf16 v[94:97], v[148:151], v[196:199], v[94:97]
	v_mfma_f32_16x16x32_bf16 v[86:89], v[156:159], v[196:199], v[86:89]
	v_mfma_f32_16x16x32_bf16 v[78:81], v[148:151], v[204:207], v[78:81]
	v_mfma_f32_16x16x32_bf16 v[70:73], v[156:159], v[204:207], v[70:73]
	s_setprio 0
	s_setprio 1
	v_mfma_f32_16x16x32_bf16 v[122:125], v[160:163], v[176:179], v[122:125]
	v_mfma_f32_16x16x32_bf16 v[114:117], v[168:171], v[176:179], v[114:117]
	v_mfma_f32_16x16x32_bf16 v[106:109], v[160:163], v[184:187], v[106:109]
	v_mfma_f32_16x16x32_bf16 v[98:101], v[168:171], v[184:187], v[98:101]
	v_mfma_f32_16x16x32_bf16 v[90:93], v[160:163], v[192:195], v[90:93]
	v_mfma_f32_16x16x32_bf16 v[82:85], v[168:171], v[192:195], v[82:85]
	v_mfma_f32_16x16x32_bf16 v[74:77], v[160:163], v[200:203], v[74:77]
	v_mfma_f32_16x16x32_bf16 v[66:69], v[168:171], v[200:203], v[66:69]
	v_mfma_f32_16x16x32_bf16 v[122:125], v[164:167], v[180:183], v[122:125]
	v_mfma_f32_16x16x32_bf16 v[114:117], v[172:175], v[180:183], v[114:117]
	v_mfma_f32_16x16x32_bf16 v[106:109], v[164:167], v[188:191], v[106:109]
	v_mfma_f32_16x16x32_bf16 v[98:101], v[172:175], v[188:191], v[98:101]
	v_mfma_f32_16x16x32_bf16 v[90:93], v[164:167], v[196:199], v[90:93]
	v_mfma_f32_16x16x32_bf16 v[82:85], v[172:175], v[196:199], v[82:85]
	v_mfma_f32_16x16x32_bf16 v[74:77], v[164:167], v[204:207], v[74:77]
	v_mfma_f32_16x16x32_bf16 v[66:69], v[172:175], v[204:207], v[66:69]
	s_setprio 0
	s_barrier
	s_add_i32 s52, s52, s39
	v_lshl_add_u64 v[210:211], s[28:29], 0, v[0:1]
	s_mov_b32 m0, s52
	ds_read_b128 v[176:179], v143 offset:16384
	ds_read_b128 v[180:183], v143 offset:17408
	ds_read_b128 v[184:187], v143 offset:18432
	ds_read_b128 v[188:191], v143 offset:19456
	ds_read_b128 v[192:195], v143 offset:20480
	ds_read_b128 v[196:199], v143 offset:21504
	ds_read_b128 v[200:203], v143 offset:22528
	ds_read_b128 v[204:207], v143 offset:23552
	global_load_lds_dwordx4 v[210:211], off
	s_add_i32 m0, s52, 0x2000
	s_add_u32 s52, s28, 0x40000
	v_lshl_add_u64 v[214:215], s[28:29], 0, v[130:131]
	s_addc_u32 s53, s29, 0
	s_add_i32 s54, s54, s39
	global_load_lds_dwordx4 v[214:215], off
	v_lshl_add_u64 v[216:217], s[52:53], 0, v[0:1]
	s_mov_b32 m0, s54
	v_lshl_add_u64 v[224:225], s[30:31], 0, v[132:133]
	global_load_lds_dwordx4 v[216:217], off
	v_lshl_add_u64 v[216:217], s[52:53], 0, v[130:131]
	s_add_i32 m0, s54, 0x2000
	s_nop 0
	global_load_lds_dwordx4 v[216:217], off
	v_lshl_add_u64 v[216:217], s[30:31], 0, v[134:135]
	s_mov_b32 m0, s25
	s_nop 0
	global_load_lds_dwordx4 v[216:217], off
	s_mov_b32 m0, s40
	s_nop 0
	global_load_lds_dwordx4 v[224:225], off
	s_waitcnt vmcnt(8)
	s_waitcnt lgkmcnt(0)
	s_barrier
	s_setprio 1
	s_waitcnt lgkmcnt(0)
	v_mfma_f32_16x16x32_bf16 v[62:65], v[144:147], v[176:179], v[62:65]
	v_mfma_f32_16x16x32_bf16 v[54:57], v[152:155], v[176:179], v[54:57]
	v_mfma_f32_16x16x32_bf16 v[46:49], v[144:147], v[184:187], v[46:49]
	v_mfma_f32_16x16x32_bf16 v[38:41], v[152:155], v[184:187], v[38:41]
	v_mfma_f32_16x16x32_bf16 v[30:33], v[144:147], v[192:195], v[30:33]
	v_mfma_f32_16x16x32_bf16 v[22:25], v[152:155], v[192:195], v[22:25]
	v_mfma_f32_16x16x32_bf16 v[14:17], v[144:147], v[200:203], v[14:17]
	v_mfma_f32_16x16x32_bf16 v[6:9], v[152:155], v[200:203], v[6:9]
	v_mfma_f32_16x16x32_bf16 v[62:65], v[148:151], v[180:183], v[62:65]
	v_mfma_f32_16x16x32_bf16 v[54:57], v[156:159], v[180:183], v[54:57]
	v_mfma_f32_16x16x32_bf16 v[46:49], v[148:151], v[188:191], v[46:49]
	v_mfma_f32_16x16x32_bf16 v[38:41], v[156:159], v[188:191], v[38:41]
	v_mfma_f32_16x16x32_bf16 v[30:33], v[148:151], v[196:199], v[30:33]
	v_mfma_f32_16x16x32_bf16 v[22:25], v[156:159], v[196:199], v[22:25]
	v_mfma_f32_16x16x32_bf16 v[14:17], v[148:151], v[204:207], v[14:17]
	v_mfma_f32_16x16x32_bf16 v[6:9], v[156:159], v[204:207], v[6:9]
	s_setprio 0
	s_setprio 1
	v_mfma_f32_16x16x32_bf16 v[58:61], v[160:163], v[176:179], v[58:61]
	v_mfma_f32_16x16x32_bf16 v[50:53], v[168:171], v[176:179], v[50:53]
	v_mfma_f32_16x16x32_bf16 v[42:45], v[160:163], v[184:187], v[42:45]
	v_mfma_f32_16x16x32_bf16 v[34:37], v[168:171], v[184:187], v[34:37]
	v_mfma_f32_16x16x32_bf16 v[26:29], v[160:163], v[192:195], v[26:29]
	v_mfma_f32_16x16x32_bf16 v[18:21], v[168:171], v[192:195], v[18:21]
	v_mfma_f32_16x16x32_bf16 v[10:13], v[160:163], v[200:203], v[10:13]
	v_mfma_f32_16x16x32_bf16 v[2:5], v[168:171], v[200:203], v[2:5]
	v_mfma_f32_16x16x32_bf16 v[58:61], v[164:167], v[180:183], v[58:61]
	v_mfma_f32_16x16x32_bf16 v[50:53], v[172:175], v[180:183], v[50:53]
	v_mfma_f32_16x16x32_bf16 v[42:45], v[164:167], v[188:191], v[42:45]
	v_mfma_f32_16x16x32_bf16 v[34:37], v[172:175], v[188:191], v[34:37]
	v_mfma_f32_16x16x32_bf16 v[26:29], v[164:167], v[196:199], v[26:29]
	v_mfma_f32_16x16x32_bf16 v[18:21], v[172:175], v[196:199], v[18:21]
	v_mfma_f32_16x16x32_bf16 v[10:13], v[164:167], v[204:207], v[10:13]
	v_mfma_f32_16x16x32_bf16 v[2:5], v[172:175], v[204:207], v[2:5]
	s_setprio 0
	s_barrier
	s_add_i32 s52, 0, 0x18000
	v_add_u32_e32 v140, s52, v141
	s_add_i32 s53, 0, 0x1c000
	ds_read_b128 v[144:147], v140
	ds_read_b128 v[148:151], v140 offset:1024
	ds_read_b128 v[152:155], v140 offset:2048
	ds_read_b128 v[156:159], v140 offset:3072
	v_add_u32_e32 v140, s53, v141
	ds_read_b128 v[160:163], v140
	ds_read_b128 v[164:167], v140 offset:1024
	ds_read_b128 v[168:171], v140 offset:2048
	ds_read_b128 v[172:175], v140 offset:3072
	s_add_u32 s30, s30, 0x40000
	s_addc_u32 s31, s31, 0
	s_mov_b32 m0, s41
	v_lshl_add_u64 v[226:227], s[30:31], 0, v[134:135]
	ds_read_b128 v[176:179], v143 offset:32768
	ds_read_b128 v[180:183], v143 offset:33792
	ds_read_b128 v[184:187], v143 offset:34816
	ds_read_b128 v[188:191], v143 offset:35840
	ds_read_b128 v[192:195], v143 offset:36864
	ds_read_b128 v[196:199], v143 offset:37888
	ds_read_b128 v[200:203], v143 offset:38912
	ds_read_b128 v[204:207], v143 offset:39936
	global_load_lds_dwordx4 v[226:227], off
	v_lshl_add_u64 v[226:227], s[30:31], 0, v[132:133]
	s_mov_b32 m0, s42
	s_nop 0
	global_load_lds_dwordx4 v[226:227], off
	s_waitcnt vmcnt(8)
	s_waitcnt lgkmcnt(0)
	s_barrier
	s_setprio 1
	s_waitcnt lgkmcnt(0)
	v_mfma_f32_16x16x32_bf16 v[126:129], v[144:147], v[176:179], v[126:129]
	v_mfma_f32_16x16x32_bf16 v[118:121], v[152:155], v[176:179], v[118:121]
	v_mfma_f32_16x16x32_bf16 v[110:113], v[144:147], v[184:187], v[110:113]
	v_mfma_f32_16x16x32_bf16 v[102:105], v[152:155], v[184:187], v[102:105]
	v_mfma_f32_16x16x32_bf16 v[94:97], v[144:147], v[192:195], v[94:97]
	v_mfma_f32_16x16x32_bf16 v[86:89], v[152:155], v[192:195], v[86:89]
	v_mfma_f32_16x16x32_bf16 v[78:81], v[144:147], v[200:203], v[78:81]
	v_mfma_f32_16x16x32_bf16 v[70:73], v[152:155], v[200:203], v[70:73]
	v_mfma_f32_16x16x32_bf16 v[126:129], v[148:151], v[180:183], v[126:129]
	v_mfma_f32_16x16x32_bf16 v[118:121], v[156:159], v[180:183], v[118:121]
	v_mfma_f32_16x16x32_bf16 v[110:113], v[148:151], v[188:191], v[110:113]
	v_mfma_f32_16x16x32_bf16 v[102:105], v[156:159], v[188:191], v[102:105]
	v_mfma_f32_16x16x32_bf16 v[94:97], v[148:151], v[196:199], v[94:97]
	v_mfma_f32_16x16x32_bf16 v[86:89], v[156:159], v[196:199], v[86:89]
	v_mfma_f32_16x16x32_bf16 v[78:81], v[148:151], v[204:207], v[78:81]
	v_mfma_f32_16x16x32_bf16 v[70:73], v[156:159], v[204:207], v[70:73]
	s_setprio 0
	s_setprio 1
	v_mfma_f32_16x16x32_bf16 v[122:125], v[160:163], v[176:179], v[122:125]
	v_mfma_f32_16x16x32_bf16 v[114:117], v[168:171], v[176:179], v[114:117]
	v_mfma_f32_16x16x32_bf16 v[106:109], v[160:163], v[184:187], v[106:109]
	v_mfma_f32_16x16x32_bf16 v[98:101], v[168:171], v[184:187], v[98:101]
	v_mfma_f32_16x16x32_bf16 v[90:93], v[160:163], v[192:195], v[90:93]
	v_mfma_f32_16x16x32_bf16 v[82:85], v[168:171], v[192:195], v[82:85]
	v_mfma_f32_16x16x32_bf16 v[74:77], v[160:163], v[200:203], v[74:77]
	v_mfma_f32_16x16x32_bf16 v[66:69], v[168:171], v[200:203], v[66:69]
	v_mfma_f32_16x16x32_bf16 v[122:125], v[164:167], v[180:183], v[122:125]
	v_mfma_f32_16x16x32_bf16 v[114:117], v[172:175], v[180:183], v[114:117]
	v_mfma_f32_16x16x32_bf16 v[106:109], v[164:167], v[188:191], v[106:109]
	v_mfma_f32_16x16x32_bf16 v[98:101], v[172:175], v[188:191], v[98:101]
	v_mfma_f32_16x16x32_bf16 v[90:93], v[164:167], v[196:199], v[90:93]
	v_mfma_f32_16x16x32_bf16 v[82:85], v[172:175], v[196:199], v[82:85]
	v_mfma_f32_16x16x32_bf16 v[74:77], v[164:167], v[204:207], v[74:77]
	v_mfma_f32_16x16x32_bf16 v[66:69], v[172:175], v[204:207], v[66:69]
	s_setprio 0
	s_barrier
	s_add_i32 s30, s52, s39
	v_lshl_add_u64 v[210:211], v[210:211], 0, s[94:95]
	s_mov_b32 m0, s30
	ds_read_b128 v[176:179], v143 offset:49152
	ds_read_b128 v[180:183], v143 offset:50176
	ds_read_b128 v[184:187], v143 offset:51200
	ds_read_b128 v[188:191], v143 offset:52224
	ds_read_b128 v[192:195], v143 offset:53248
	ds_read_b128 v[196:199], v143 offset:54272
	ds_read_b128 v[200:203], v143 offset:55296
	ds_read_b128 v[204:207], v143 offset:56320
	global_load_lds_dwordx4 v[210:211], off
	s_add_i32 m0, s30, 0x2000
	s_add_u32 s28, s28, 0x40080
	v_lshl_add_u64 v[210:211], v[214:215], 0, s[94:95]
	s_addc_u32 s29, s29, 0
	s_add_i32 s30, s53, s39
	global_load_lds_dwordx4 v[210:211], off
	v_lshl_add_u64 v[210:211], s[28:29], 0, v[0:1]
	s_mov_b32 m0, s30
	s_nop 0
	global_load_lds_dwordx4 v[210:211], off
	v_lshl_add_u64 v[210:211], s[28:29], 0, v[130:131]
	s_add_i32 m0, s30, 0x2000
	s_nop 0
	global_load_lds_dwordx4 v[210:211], off
	v_lshl_add_u64 v[210:211], v[216:217], 0, s[94:95]
	s_mov_b32 m0, s45
	s_nop 0
	global_load_lds_dwordx4 v[210:211], off
	v_lshl_add_u64 v[210:211], v[224:225], 0, s[94:95]
	s_mov_b32 m0, s46
	s_nop 0
	global_load_lds_dwordx4 v[210:211], off
	s_waitcnt vmcnt(8)
	s_waitcnt lgkmcnt(0)
	s_barrier
	s_setprio 1
	s_waitcnt lgkmcnt(0)
	v_mfma_f32_16x16x32_bf16 v[62:65], v[144:147], v[176:179], v[62:65]
	v_mfma_f32_16x16x32_bf16 v[54:57], v[152:155], v[176:179], v[54:57]
	v_mfma_f32_16x16x32_bf16 v[46:49], v[144:147], v[184:187], v[46:49]
	v_mfma_f32_16x16x32_bf16 v[38:41], v[152:155], v[184:187], v[38:41]
	v_mfma_f32_16x16x32_bf16 v[30:33], v[144:147], v[192:195], v[30:33]
	v_mfma_f32_16x16x32_bf16 v[22:25], v[152:155], v[192:195], v[22:25]
	v_mfma_f32_16x16x32_bf16 v[14:17], v[144:147], v[200:203], v[14:17]
	v_mfma_f32_16x16x32_bf16 v[6:9], v[152:155], v[200:203], v[6:9]
	v_mfma_f32_16x16x32_bf16 v[62:65], v[148:151], v[180:183], v[62:65]
	v_mfma_f32_16x16x32_bf16 v[54:57], v[156:159], v[180:183], v[54:57]
	v_mfma_f32_16x16x32_bf16 v[46:49], v[148:151], v[188:191], v[46:49]
	v_mfma_f32_16x16x32_bf16 v[38:41], v[156:159], v[188:191], v[38:41]
	v_mfma_f32_16x16x32_bf16 v[30:33], v[148:151], v[196:199], v[30:33]
	v_mfma_f32_16x16x32_bf16 v[22:25], v[156:159], v[196:199], v[22:25]
	v_mfma_f32_16x16x32_bf16 v[14:17], v[148:151], v[204:207], v[14:17]
	v_mfma_f32_16x16x32_bf16 v[6:9], v[156:159], v[204:207], v[6:9]
	s_setprio 0
	s_setprio 1
	v_mfma_f32_16x16x32_bf16 v[58:61], v[160:163], v[176:179], v[58:61]
	v_mfma_f32_16x16x32_bf16 v[50:53], v[168:171], v[176:179], v[50:53]
	v_mfma_f32_16x16x32_bf16 v[42:45], v[160:163], v[184:187], v[42:45]
	v_mfma_f32_16x16x32_bf16 v[34:37], v[168:171], v[184:187], v[34:37]
	v_mfma_f32_16x16x32_bf16 v[26:29], v[160:163], v[192:195], v[26:29]
	v_mfma_f32_16x16x32_bf16 v[18:21], v[168:171], v[192:195], v[18:21]
	v_mfma_f32_16x16x32_bf16 v[10:13], v[160:163], v[200:203], v[10:13]
	v_mfma_f32_16x16x32_bf16 v[2:5], v[168:171], v[200:203], v[2:5]
	v_mfma_f32_16x16x32_bf16 v[58:61], v[164:167], v[180:183], v[58:61]
	v_mfma_f32_16x16x32_bf16 v[50:53], v[172:175], v[180:183], v[50:53]
	v_mfma_f32_16x16x32_bf16 v[42:45], v[164:167], v[188:191], v[42:45]
	v_mfma_f32_16x16x32_bf16 v[34:37], v[172:175], v[188:191], v[34:37]
	v_mfma_f32_16x16x32_bf16 v[26:29], v[164:167], v[196:199], v[26:29]
	v_mfma_f32_16x16x32_bf16 v[18:21], v[172:175], v[196:199], v[18:21]
	v_mfma_f32_16x16x32_bf16 v[10:13], v[164:167], v[204:207], v[10:13]
	v_mfma_f32_16x16x32_bf16 v[2:5], v[172:175], v[204:207], v[2:5]
	s_setprio 0
	s_barrier
	s_add_i32 s51, s51, 2
	s_add_u32 s26, s26, 0x100
	s_addc_u32 s27, s27, 0
	s_add_u32 s49, s49, 0x100
	s_addc_u32 s50, s50, 0
	s_cmp_gt_u32 s51, 13
	s_cbranch_scc0 .LBB0_1238
	v_mov_b32_e32 v140, v212
	s_lshl_b32 s13, s24, 7
	v_and_b32_e32 v153, 15, v140
	v_ashrrev_i32_e32 v140, 4, v140
	s_or_b32 s13, s13, s44
	v_lshl_add_u32 v152, v140, 3, s13
	s_lshl_b32 s13, s22, 8
	s_add_i32 s15, s13, s43
	v_or_b32_e32 v158, s15, v153
	v_lshlrev_b32_e32 v144, 2, v140
	v_ashrrev_i32_e32 v145, 31, v144
	v_ashrrev_i32_e32 v159, 31, v158
	v_or_b32_e32 v148, 16, v158
	v_lshl_add_u64 v[160:161], v[144:145], 2, s[4:5]
	v_lshlrev_b64 v[144:145], 6, v[158:159]
	v_ashrrev_i32_e32 v149, 31, v148
	v_or_b32_e32 v154, 32, v158
	v_lshl_add_u64 v[162:163], v[160:161], 0, v[144:145]
	v_lshlrev_b64 v[148:149], 6, v[148:149]
	v_ashrrev_i32_e32 v155, 31, v154
	v_or_b32_e32 v158, 48, v158
	global_load_dwordx4 v[144:147], v[162:163], off
	v_lshl_add_u64 v[148:149], v[160:161], 0, v[148:149]
	v_lshlrev_b64 v[154:155], 6, v[154:155]
	v_ashrrev_i32_e32 v159, 31, v158
	global_load_dwordx4 v[148:151], v[148:149], off
	v_lshl_add_u64 v[154:155], v[160:161], 0, v[154:155]
	v_lshlrev_b64 v[158:159], 6, v[158:159]
	global_load_dwordx4 v[154:157], v[154:155], off
	v_lshl_add_u64 v[158:159], v[160:161], 0, v[158:159]
	global_load_dwordx4 v[158:161], v[158:159], off
	s_movk_i32 s15, 0x2000
	v_add_co_u32_e32 v174, vcc, s15, v162
	s_nop 1
	v_addc_co_u32_e32 v175, vcc, 0, v163, vcc
	global_load_dwordx4 v[162:165], v[174:175], off
	global_load_dwordx4 v[166:169], v[174:175], off offset:1024
	global_load_dwordx4 v[170:173], v[174:175], off offset:2048
	s_nop 0
	global_load_dwordx4 v[174:177], v[174:175], off offset:3072
	s_and_b64 vcc, exec, s[8:9]
	s_cbranch_vccz .LBB0_1241
	s_barrier
.LBB0_1241:
	s_waitcnt vmcnt(4)
	v_add_f32_e32 v140, v144, v145
	v_add_f32_e32 v142, v146, v147
	v_add_f32_e32 v140, v140, v142
	v_add_f32_e32 v142, v148, v149
	v_add_f32_e32 v144, v150, v151
	v_add_f32_e32 v142, v142, v144
	v_add_f32_e32 v144, v154, v155
	v_add_f32_e32 v145, v156, v157
	v_add_f32_e32 v144, v144, v145
	v_add_f32_e32 v145, v158, v159
	v_add_f32_e32 v146, v160, v161
	v_add_f32_e32 v145, v145, v146
	s_andn2_b64 vcc, exec, s[16:17]
	s_waitcnt vmcnt(3)
	v_add_f32_e32 v146, v162, v163
	v_add_f32_e32 v147, v164, v165
	v_add_f32_e32 v146, v146, v147
	s_waitcnt vmcnt(2)
	v_add_f32_e32 v147, v166, v167
	v_add_f32_e32 v148, v168, v169
	v_add_f32_e32 v147, v147, v148
	s_waitcnt vmcnt(1)
	v_add_f32_e32 v148, v170, v171
	v_add_f32_e32 v149, v172, v173
	v_add_f32_e32 v148, v148, v149
	s_waitcnt vmcnt(0)
	v_add_f32_e32 v149, v174, v175
	v_add_f32_e32 v150, v176, v177
	v_add_f32_e32 v149, v149, v150
	v_mov_b32_e32 v150, v140
	s_nop 1
	v_permlane16_swap_b32_e32 v140, v150
	v_add_f32_e32 v140, v140, v150
	v_mov_b32_e32 v150, v142
	s_nop 1
	v_permlane16_swap_b32_e32 v142, v150
	v_add_f32_e32 v142, v142, v150
	v_mov_b32_e32 v150, v144
	s_nop 1
	v_permlane16_swap_b32_e32 v144, v150
	v_add_f32_e32 v144, v144, v150
	v_mov_b32_e32 v150, v145
	s_nop 1
	v_permlane16_swap_b32_e32 v145, v150
	v_add_f32_e32 v145, v145, v150
	v_mov_b32_e32 v150, v146
	s_nop 1
	v_permlane16_swap_b32_e32 v146, v150
	v_add_f32_e32 v146, v146, v150
	v_mov_b32_e32 v150, v147
	s_nop 1
	v_permlane16_swap_b32_e32 v147, v150
	v_add_f32_e32 v147, v147, v150
	v_mov_b32_e32 v150, v148
	s_nop 1
	v_permlane16_swap_b32_e32 v148, v150
	v_add_f32_e32 v148, v148, v150
	v_mov_b32_e32 v150, v149
	s_nop 1
	v_permlane16_swap_b32_e32 v149, v150
	v_add_f32_e32 v149, v149, v150
	v_mov_b32_e32 v150, v140
	s_nop 1
	v_permlane32_swap_b32_e32 v140, v150
	v_add_f32_e32 v140, v140, v150
	v_mov_b32_e32 v150, v142
	s_nop 1
	v_permlane32_swap_b32_e32 v142, v150
	v_add_f32_e32 v142, v142, v150
	v_mov_b32_e32 v150, v144
	s_nop 1
	v_permlane32_swap_b32_e32 v144, v150
	v_add_f32_e32 v144, v144, v150
	v_mov_b32_e32 v150, v145
	s_nop 1
	v_permlane32_swap_b32_e32 v145, v150
	v_add_f32_e32 v145, v145, v150
	v_mov_b32_e32 v150, v146
	s_nop 1
	v_permlane32_swap_b32_e32 v146, v150
	v_add_f32_e32 v146, v146, v150
	v_mov_b32_e32 v150, v147
	s_nop 1
	v_permlane32_swap_b32_e32 v147, v150
	v_fmamk_f32 v140, v140, 0x3a800000, v213
	v_add_f32_e32 v147, v147, v150
	v_mov_b32_e32 v150, v148
	v_rsq_f32_e32 v156, v140
	s_nop 0
	v_permlane32_swap_b32_e32 v148, v150
	v_fmamk_f32 v140, v142, 0x3a800000, v213
	v_add_f32_e32 v151, v148, v150
	v_mov_b32_e32 v148, v149
	v_rsq_f32_e32 v154, v140
	v_fmamk_f32 v140, v144, 0x3a800000, v213
	v_permlane32_swap_b32_e32 v149, v148
	v_rsq_f32_e32 v150, v140
	v_fmamk_f32 v140, v145, 0x3a800000, v213
	v_add_f32_e32 v149, v149, v148
	v_rsq_f32_e32 v148, v140
	v_fmamk_f32 v140, v146, 0x3a800000, v213
	v_pk_mul_f32 v[126:127], v[126:127], v[156:157] op_sel_hi:[1,0]
	v_rsq_f32_e32 v146, v140
	v_fmamk_f32 v140, v147, 0x3a800000, v213
	v_mul_f32_e32 v147, 0xbfb8aa3b, v126
	v_exp_f32_e32 v147, v147
	v_pk_mul_f32 v[122:123], v[122:123], v[156:157] op_sel_hi:[1,0]
	v_pk_mul_f32 v[124:125], v[124:125], v[156:157] op_sel_hi:[1,0]
	v_pk_mul_f32 v[118:119], v[118:119], v[156:157] op_sel_hi:[1,0]
	v_add_f32_e32 v147, 1.0, v147
	v_rcp_f32_e32 v158, v147
	v_mul_f32_e32 v147, 0xbfb8aa3b, v127
	v_exp_f32_e32 v147, v147
	v_pk_mul_f32 v[114:115], v[114:115], v[156:157] op_sel_hi:[1,0]
	v_pk_mul_f32 v[116:117], v[116:117], v[156:157] op_sel_hi:[1,0]
	v_pk_mul_f32 v[110:111], v[110:111], v[154:155] op_sel_hi:[1,0]
	v_add_f32_e32 v147, 1.0, v147
	v_rcp_f32_e32 v159, v147
	v_or_b32_e32 v145, s43, v153
	v_ashrrev_i32_e32 v153, 31, v152
	v_pk_mul_f32 v[106:107], v[106:107], v[154:155] op_sel_hi:[1,0]
	v_pk_mul_f32 v[126:127], v[126:127], v[158:159]
	v_pk_mul_f32 v[108:109], v[108:109], v[154:155] op_sel_hi:[1,0]
	v_pk_mul_f32 v[122:123], v[122:123], v[126:127]
	v_pk_mul_f32 v[126:127], v[128:129], v[156:157] op_sel_hi:[1,0]
	v_cvt_pk_bf16_f32 v122, v122, v123
	v_mul_f32_e32 v128, 0xbfb8aa3b, v126
	v_mul_f32_e32 v129, 0xbfb8aa3b, v127
	v_exp_f32_e32 v128, v128
	v_exp_f32_e32 v129, v129
	v_pk_mul_f32 v[102:103], v[102:103], v[154:155] op_sel_hi:[1,0]
	v_pk_mul_f32 v[98:99], v[98:99], v[154:155] op_sel_hi:[1,0]
	v_add_f32_e32 v128, 1.0, v128
	v_add_f32_e32 v129, 1.0, v129
	v_rcp_f32_e32 v128, v128
	v_rcp_f32_e32 v129, v129
	v_pk_mul_f32 v[100:101], v[100:101], v[154:155] op_sel_hi:[1,0]
	v_pk_mul_f32 v[94:95], v[94:95], v[150:151] op_sel_hi:[1,0]
	v_pk_mul_f32 v[90:91], v[90:91], v[150:151] op_sel_hi:[1,0]
	v_pk_mul_f32 v[126:127], v[126:127], v[128:129]
	v_pk_mul_f32 v[92:93], v[92:93], v[150:151] op_sel_hi:[1,0]
	v_pk_mul_f32 v[124:125], v[124:125], v[126:127]
	v_pk_mul_f32 v[86:87], v[86:87], v[150:151] op_sel_hi:[1,0]
	v_cvt_pk_bf16_f32 v123, v124, v125
	v_mul_f32_e32 v124, 0xbfb8aa3b, v118
	v_mul_f32_e32 v125, 0xbfb8aa3b, v119
	v_exp_f32_e32 v124, v124
	v_exp_f32_e32 v125, v125
	v_pk_mul_f32 v[82:83], v[82:83], v[150:151] op_sel_hi:[1,0]
	v_pk_mul_f32 v[84:85], v[84:85], v[150:151] op_sel_hi:[1,0]
	v_add_f32_e32 v124, 1.0, v124
	v_add_f32_e32 v125, 1.0, v125
	v_rcp_f32_e32 v124, v124
	v_rcp_f32_e32 v125, v125
	v_pk_mul_f32 v[78:79], v[78:79], v[148:149] op_sel_hi:[1,0]
	v_pk_mul_f32 v[74:75], v[74:75], v[148:149] op_sel_hi:[1,0]
	v_pk_mul_f32 v[76:77], v[76:77], v[148:149] op_sel_hi:[1,0]
	v_pk_mul_f32 v[118:119], v[118:119], v[124:125]
	v_pk_mul_f32 v[70:71], v[70:71], v[148:149] op_sel_hi:[1,0]
	v_pk_mul_f32 v[114:115], v[114:115], v[118:119]
	v_pk_mul_f32 v[118:119], v[120:121], v[156:157] op_sel_hi:[1,0]
	v_cvt_pk_bf16_f32 v124, v114, v115
	v_mul_f32_e32 v120, 0xbfb8aa3b, v118
	v_mul_f32_e32 v121, 0xbfb8aa3b, v119
	v_exp_f32_e32 v120, v120
	v_exp_f32_e32 v121, v121
	v_mov_b64_e32 v[114:115], s[6:7]
	v_pk_mul_f32 v[66:67], v[66:67], v[148:149] op_sel_hi:[1,0]
	v_add_f32_e32 v120, 1.0, v120
	v_add_f32_e32 v121, 1.0, v121
	v_rcp_f32_e32 v120, v120
	v_rcp_f32_e32 v121, v121
	v_pk_mul_f32 v[68:69], v[68:69], v[148:149] op_sel_hi:[1,0]
	v_pk_mul_f32 v[62:63], v[62:63], v[146:147] op_sel_hi:[1,0]
	v_pk_mul_f32 v[58:59], v[58:59], v[146:147] op_sel_hi:[1,0]
	v_pk_mul_f32 v[118:119], v[118:119], v[120:121]
	v_pk_mul_f32 v[60:61], v[60:61], v[146:147] op_sel_hi:[1,0]
	v_pk_mul_f32 v[116:117], v[116:117], v[118:119]
	v_mul_f32_e32 v119, 0xbfb8aa3b, v110
	v_exp_f32_e32 v119, v119
	v_add_u32_e32 v118, s13, v145
	v_cvt_pk_bf16_f32 v125, v116, v117
	v_mad_i64_i32 v[120:121], s[22:23], v118, s66, v[114:115]
	v_lshlrev_b64 v[116:117], 1, v[152:153]
	v_lshl_add_u64 v[120:121], v[120:121], 0, v[116:117]
	v_add_f32_e32 v119, 1.0, v119
	global_store_dwordx4 v[120:121], v[122:125], off
	v_rcp_f32_e32 v120, v119
	v_mul_f32_e32 v119, 0xbfb8aa3b, v111
	v_exp_f32_e32 v119, v119
	v_pk_mul_f32 v[54:55], v[54:55], v[146:147] op_sel_hi:[1,0]
	v_pk_mul_f32 v[50:51], v[50:51], v[146:147] op_sel_hi:[1,0]
	v_rsq_f32_e32 v144, v140
	v_add_f32_e32 v119, 1.0, v119
	v_rcp_f32_e32 v121, v119
	v_pk_mul_f32 v[52:53], v[52:53], v[146:147] op_sel_hi:[1,0]
	v_pk_mul_f32 v[46:47], v[46:47], v[144:145] op_sel_hi:[1,0]
	v_pk_mul_f32 v[42:43], v[42:43], v[144:145] op_sel_hi:[1,0]
	v_pk_mul_f32 v[110:111], v[110:111], v[120:121]
	v_pk_mul_f32 v[44:45], v[44:45], v[144:145] op_sel_hi:[1,0]
	v_pk_mul_f32 v[106:107], v[106:107], v[110:111]
	v_pk_mul_f32 v[110:111], v[112:113], v[154:155] op_sel_hi:[1,0]
	v_cvt_pk_bf16_f32 v106, v106, v107
	v_mul_f32_e32 v112, 0xbfb8aa3b, v110
	v_mul_f32_e32 v113, 0xbfb8aa3b, v111
	v_exp_f32_e32 v112, v112
	v_exp_f32_e32 v113, v113
	v_pk_mul_f32 v[38:39], v[38:39], v[144:145] op_sel_hi:[1,0]
	v_pk_mul_f32 v[34:35], v[34:35], v[144:145] op_sel_hi:[1,0]
	v_add_f32_e32 v112, 1.0, v112
	v_add_f32_e32 v113, 1.0, v113
	v_rcp_f32_e32 v112, v112
	v_rcp_f32_e32 v113, v113
	v_fmamk_f32 v140, v151, 0x3a800000, v213
	v_rsq_f32_e32 v142, v140
	v_pk_mul_f32 v[36:37], v[36:37], v[144:145] op_sel_hi:[1,0]
	v_pk_mul_f32 v[110:111], v[110:111], v[112:113]
	v_fmamk_f32 v140, v149, 0x3a800000, v213
	v_pk_mul_f32 v[108:109], v[108:109], v[110:111]
	v_pk_mul_f32 v[30:31], v[30:31], v[142:143] op_sel_hi:[1,0]
	v_cvt_pk_bf16_f32 v107, v108, v109
	v_mul_f32_e32 v108, 0xbfb8aa3b, v102
	v_mul_f32_e32 v109, 0xbfb8aa3b, v103
	v_exp_f32_e32 v108, v108
	v_exp_f32_e32 v109, v109
	v_pk_mul_f32 v[26:27], v[26:27], v[142:143] op_sel_hi:[1,0]
	v_pk_mul_f32 v[28:29], v[28:29], v[142:143] op_sel_hi:[1,0]
	v_add_f32_e32 v108, 1.0, v108
	v_add_f32_e32 v109, 1.0, v109
	v_rcp_f32_e32 v108, v108
	v_rcp_f32_e32 v109, v109
	v_pk_mul_f32 v[22:23], v[22:23], v[142:143] op_sel_hi:[1,0]
	v_pk_mul_f32 v[18:19], v[18:19], v[142:143] op_sel_hi:[1,0]
	v_rsq_f32_e32 v140, v140
	v_pk_mul_f32 v[102:103], v[102:103], v[108:109]
	v_pk_mul_f32 v[20:21], v[20:21], v[142:143] op_sel_hi:[1,0]
	v_pk_mul_f32 v[98:99], v[98:99], v[102:103]
	v_pk_mul_f32 v[102:103], v[104:105], v[154:155] op_sel_hi:[1,0]
	v_cvt_pk_bf16_f32 v108, v98, v99
	v_mul_f32_e32 v104, 0xbfb8aa3b, v102
	v_mul_f32_e32 v105, 0xbfb8aa3b, v103
	v_exp_f32_e32 v104, v104
	v_exp_f32_e32 v105, v105
	v_or_b32_e32 v98, 16, v118
	v_mad_i64_i32 v[98:99], s[22:23], v98, s66, v[114:115]
	v_add_f32_e32 v104, 1.0, v104
	v_add_f32_e32 v105, 1.0, v105
	v_rcp_f32_e32 v104, v104
	v_rcp_f32_e32 v105, v105
	v_lshl_add_u64 v[98:99], v[98:99], 0, v[116:117]
	v_pk_mul_f32 v[14:15], v[14:15], v[140:141] op_sel_hi:[1,0]
	v_pk_mul_f32 v[10:11], v[10:11], v[140:141] op_sel_hi:[1,0]
	v_pk_mul_f32 v[102:103], v[102:103], v[104:105]
	v_pk_mul_f32 v[12:13], v[12:13], v[140:141] op_sel_hi:[1,0]
	v_pk_mul_f32 v[100:101], v[100:101], v[102:103]
	v_pk_mul_f32 v[6:7], v[6:7], v[140:141] op_sel_hi:[1,0]
	v_cvt_pk_bf16_f32 v109, v100, v101
	global_store_dwordx4 v[98:99], v[106:109], off
	v_mul_f32_e32 v98, 0xbfb8aa3b, v94
	v_mul_f32_e32 v99, 0xbfb8aa3b, v95
	v_exp_f32_e32 v98, v98
	v_exp_f32_e32 v99, v99
	v_pk_mul_f32 v[2:3], v[2:3], v[140:141] op_sel_hi:[1,0]
	v_pk_mul_f32 v[4:5], v[4:5], v[140:141] op_sel_hi:[1,0]
	v_add_f32_e32 v98, 1.0, v98
	v_add_f32_e32 v99, 1.0, v99
	v_rcp_f32_e32 v98, v98
	v_rcp_f32_e32 v99, v99
	s_nop 0
	v_pk_mul_f32 v[94:95], v[94:95], v[98:99]
	s_nop 0
	v_pk_mul_f32 v[90:91], v[90:91], v[94:95]
	v_pk_mul_f32 v[94:95], v[96:97], v[150:151] op_sel_hi:[1,0]
	v_cvt_pk_bf16_f32 v90, v90, v91
	v_mul_f32_e32 v96, 0xbfb8aa3b, v94
	v_mul_f32_e32 v97, 0xbfb8aa3b, v95
	v_exp_f32_e32 v96, v96
	v_exp_f32_e32 v97, v97
	v_add_f32_e32 v96, 1.0, v96
	v_add_f32_e32 v97, 1.0, v97
	v_rcp_f32_e32 v96, v96
	v_rcp_f32_e32 v97, v97
	s_nop 0
	v_pk_mul_f32 v[94:95], v[94:95], v[96:97]
	s_nop 0
	v_pk_mul_f32 v[92:93], v[92:93], v[94:95]
	s_nop 0
	v_cvt_pk_bf16_f32 v91, v92, v93
	v_mul_f32_e32 v92, 0xbfb8aa3b, v86
	v_mul_f32_e32 v93, 0xbfb8aa3b, v87
	v_exp_f32_e32 v92, v92
	v_exp_f32_e32 v93, v93
	v_add_f32_e32 v92, 1.0, v92
	v_add_f32_e32 v93, 1.0, v93
	v_rcp_f32_e32 v92, v92
	v_rcp_f32_e32 v93, v93
	s_nop 0
	v_pk_mul_f32 v[86:87], v[86:87], v[92:93]
	s_nop 0
	v_pk_mul_f32 v[82:83], v[82:83], v[86:87]
	v_pk_mul_f32 v[86:87], v[88:89], v[150:151] op_sel_hi:[1,0]
	v_cvt_pk_bf16_f32 v92, v82, v83
	v_mul_f32_e32 v88, 0xbfb8aa3b, v86
	v_mul_f32_e32 v89, 0xbfb8aa3b, v87
	v_exp_f32_e32 v88, v88
	v_exp_f32_e32 v89, v89
	v_or_b32_e32 v82, 32, v118
	v_mad_i64_i32 v[82:83], s[22:23], v82, s66, v[114:115]
	v_add_f32_e32 v88, 1.0, v88
	v_add_f32_e32 v89, 1.0, v89
	v_rcp_f32_e32 v88, v88
	v_rcp_f32_e32 v89, v89
	v_lshl_add_u64 v[82:83], v[82:83], 0, v[116:117]
	v_pk_mul_f32 v[86:87], v[86:87], v[88:89]
	s_nop 0
	v_pk_mul_f32 v[84:85], v[84:85], v[86:87]
	s_nop 0
	v_cvt_pk_bf16_f32 v93, v84, v85
	global_store_dwordx4 v[82:83], v[90:93], off
	v_mul_f32_e32 v82, 0xbfb8aa3b, v78
	v_mul_f32_e32 v83, 0xbfb8aa3b, v79
	v_exp_f32_e32 v82, v82
	v_exp_f32_e32 v83, v83
	v_add_f32_e32 v82, 1.0, v82
	v_add_f32_e32 v83, 1.0, v83
	v_rcp_f32_e32 v82, v82
	v_rcp_f32_e32 v83, v83
	s_nop 0
	v_pk_mul_f32 v[78:79], v[78:79], v[82:83]
	s_nop 0
	v_pk_mul_f32 v[74:75], v[74:75], v[78:79]
	v_pk_mul_f32 v[78:79], v[80:81], v[148:149] op_sel_hi:[1,0]
	v_cvt_pk_bf16_f32 v74, v74, v75
	v_mul_f32_e32 v80, 0xbfb8aa3b, v78
	v_mul_f32_e32 v81, 0xbfb8aa3b, v79
	v_exp_f32_e32 v80, v80
	v_exp_f32_e32 v81, v81
	v_add_f32_e32 v80, 1.0, v80
	v_add_f32_e32 v81, 1.0, v81
	v_rcp_f32_e32 v80, v80
	v_rcp_f32_e32 v81, v81
	s_nop 0
	v_pk_mul_f32 v[78:79], v[78:79], v[80:81]
	s_nop 0
	v_pk_mul_f32 v[76:77], v[76:77], v[78:79]
	s_nop 0
	v_cvt_pk_bf16_f32 v75, v76, v77
	v_mul_f32_e32 v76, 0xbfb8aa3b, v70
	v_mul_f32_e32 v77, 0xbfb8aa3b, v71
	v_exp_f32_e32 v76, v76
	v_exp_f32_e32 v77, v77
	v_add_f32_e32 v76, 1.0, v76
	v_add_f32_e32 v77, 1.0, v77
	v_rcp_f32_e32 v76, v76
	v_rcp_f32_e32 v77, v77
	s_nop 0
	v_pk_mul_f32 v[70:71], v[70:71], v[76:77]
	s_nop 0
	v_pk_mul_f32 v[66:67], v[66:67], v[70:71]
	v_pk_mul_f32 v[70:71], v[72:73], v[148:149] op_sel_hi:[1,0]
	v_cvt_pk_bf16_f32 v76, v66, v67
	v_mul_f32_e32 v72, 0xbfb8aa3b, v70
	v_mul_f32_e32 v73, 0xbfb8aa3b, v71
	v_exp_f32_e32 v72, v72
	v_exp_f32_e32 v73, v73
	v_or_b32_e32 v66, 48, v118
	v_mad_i64_i32 v[66:67], s[22:23], v66, s66, v[114:115]
	v_add_f32_e32 v72, 1.0, v72
	v_add_f32_e32 v73, 1.0, v73
	v_rcp_f32_e32 v72, v72
	v_rcp_f32_e32 v73, v73
	v_lshl_add_u64 v[66:67], v[66:67], 0, v[116:117]
	v_pk_mul_f32 v[70:71], v[70:71], v[72:73]
	s_nop 0
	v_pk_mul_f32 v[68:69], v[68:69], v[70:71]
	s_nop 0
	v_cvt_pk_bf16_f32 v77, v68, v69
	global_store_dwordx4 v[66:67], v[74:77], off
	v_mul_f32_e32 v66, 0xbfb8aa3b, v62
	v_mul_f32_e32 v67, 0xbfb8aa3b, v63
	v_exp_f32_e32 v66, v66
	v_exp_f32_e32 v67, v67
	v_add_f32_e32 v66, 1.0, v66
	v_add_f32_e32 v67, 1.0, v67
	v_rcp_f32_e32 v66, v66
	v_rcp_f32_e32 v67, v67
	s_nop 0
	v_pk_mul_f32 v[62:63], v[62:63], v[66:67]
	s_nop 0
	v_pk_mul_f32 v[58:59], v[58:59], v[62:63]
	v_pk_mul_f32 v[62:63], v[64:65], v[146:147] op_sel_hi:[1,0]
	v_cvt_pk_bf16_f32 v58, v58, v59
	v_mul_f32_e32 v64, 0xbfb8aa3b, v62
	v_mul_f32_e32 v65, 0xbfb8aa3b, v63
	v_exp_f32_e32 v64, v64
	v_exp_f32_e32 v65, v65
	v_add_f32_e32 v64, 1.0, v64
	v_add_f32_e32 v65, 1.0, v65
	v_rcp_f32_e32 v64, v64
	v_rcp_f32_e32 v65, v65
	s_nop 0
	v_pk_mul_f32 v[62:63], v[62:63], v[64:65]
	s_nop 0
	v_pk_mul_f32 v[60:61], v[60:61], v[62:63]
	s_nop 0
	v_cvt_pk_bf16_f32 v59, v60, v61
	v_mul_f32_e32 v60, 0xbfb8aa3b, v54
	v_mul_f32_e32 v61, 0xbfb8aa3b, v55
	v_exp_f32_e32 v60, v60
	v_exp_f32_e32 v61, v61
	v_add_f32_e32 v60, 1.0, v60
	v_add_f32_e32 v61, 1.0, v61
	v_rcp_f32_e32 v60, v60
	v_rcp_f32_e32 v61, v61
	s_nop 0
	v_pk_mul_f32 v[54:55], v[54:55], v[60:61]
	s_nop 0
	v_pk_mul_f32 v[50:51], v[50:51], v[54:55]
	v_pk_mul_f32 v[54:55], v[56:57], v[146:147] op_sel_hi:[1,0]
	v_cvt_pk_bf16_f32 v60, v50, v51
	v_mul_f32_e32 v56, 0xbfb8aa3b, v54
	v_mul_f32_e32 v57, 0xbfb8aa3b, v55
	v_exp_f32_e32 v56, v56
	v_exp_f32_e32 v57, v57
	v_add_u32_e32 v50, 0x80, v118
	v_mad_i64_i32 v[50:51], s[22:23], v50, s66, v[114:115]
	v_add_f32_e32 v56, 1.0, v56
	v_add_f32_e32 v57, 1.0, v57
	v_rcp_f32_e32 v56, v56
	v_rcp_f32_e32 v57, v57
	v_lshl_add_u64 v[50:51], v[50:51], 0, v[116:117]
	v_pk_mul_f32 v[54:55], v[54:55], v[56:57]
	s_nop 0
	v_pk_mul_f32 v[52:53], v[52:53], v[54:55]
	s_nop 0
	v_cvt_pk_bf16_f32 v61, v52, v53
	global_store_dwordx4 v[50:51], v[58:61], off
	v_mul_f32_e32 v50, 0xbfb8aa3b, v46
	v_mul_f32_e32 v51, 0xbfb8aa3b, v47
	v_exp_f32_e32 v50, v50
	v_exp_f32_e32 v51, v51
	v_add_f32_e32 v50, 1.0, v50
	v_add_f32_e32 v51, 1.0, v51
	v_rcp_f32_e32 v50, v50
	v_rcp_f32_e32 v51, v51
	s_nop 0
	v_pk_mul_f32 v[46:47], v[46:47], v[50:51]
	s_nop 0
	v_pk_mul_f32 v[42:43], v[42:43], v[46:47]
	v_pk_mul_f32 v[46:47], v[48:49], v[144:145] op_sel_hi:[1,0]
	v_cvt_pk_bf16_f32 v42, v42, v43
	v_mul_f32_e32 v48, 0xbfb8aa3b, v46
	v_mul_f32_e32 v49, 0xbfb8aa3b, v47
	v_exp_f32_e32 v48, v48
	v_exp_f32_e32 v49, v49
	v_add_f32_e32 v48, 1.0, v48
	v_add_f32_e32 v49, 1.0, v49
	v_rcp_f32_e32 v48, v48
	v_rcp_f32_e32 v49, v49
	s_nop 0
	v_pk_mul_f32 v[46:47], v[46:47], v[48:49]
	s_nop 0
	v_pk_mul_f32 v[44:45], v[44:45], v[46:47]
	s_nop 0
	v_cvt_pk_bf16_f32 v43, v44, v45
	v_mul_f32_e32 v44, 0xbfb8aa3b, v38
	v_mul_f32_e32 v45, 0xbfb8aa3b, v39
	v_exp_f32_e32 v44, v44
	v_exp_f32_e32 v45, v45
	v_add_f32_e32 v44, 1.0, v44
	v_add_f32_e32 v45, 1.0, v45
	v_rcp_f32_e32 v44, v44
	v_rcp_f32_e32 v45, v45
	s_nop 0
	v_pk_mul_f32 v[38:39], v[38:39], v[44:45]
	s_nop 0
	v_pk_mul_f32 v[34:35], v[34:35], v[38:39]
	v_pk_mul_f32 v[38:39], v[40:41], v[144:145] op_sel_hi:[1,0]
	v_cvt_pk_bf16_f32 v44, v34, v35
	v_mul_f32_e32 v40, 0xbfb8aa3b, v38
	v_mul_f32_e32 v41, 0xbfb8aa3b, v39
	v_exp_f32_e32 v40, v40
	v_exp_f32_e32 v41, v41
	v_add_u32_e32 v34, 0x90, v118
	v_mad_i64_i32 v[34:35], s[22:23], v34, s66, v[114:115]
	v_add_f32_e32 v40, 1.0, v40
	v_add_f32_e32 v41, 1.0, v41
	v_rcp_f32_e32 v40, v40
	v_rcp_f32_e32 v41, v41
	v_lshl_add_u64 v[34:35], v[34:35], 0, v[116:117]
	v_pk_mul_f32 v[38:39], v[38:39], v[40:41]
	s_nop 0
	v_pk_mul_f32 v[36:37], v[36:37], v[38:39]
	s_nop 0
	v_cvt_pk_bf16_f32 v45, v36, v37
	global_store_dwordx4 v[34:35], v[42:45], off
	v_mul_f32_e32 v34, 0xbfb8aa3b, v30
	v_mul_f32_e32 v35, 0xbfb8aa3b, v31
	v_exp_f32_e32 v34, v34
	v_exp_f32_e32 v35, v35
	v_add_f32_e32 v34, 1.0, v34
	v_add_f32_e32 v35, 1.0, v35
	v_rcp_f32_e32 v34, v34
	v_rcp_f32_e32 v35, v35
	s_nop 0
	v_pk_mul_f32 v[30:31], v[30:31], v[34:35]
	s_nop 0
	v_pk_mul_f32 v[26:27], v[26:27], v[30:31]
	v_pk_mul_f32 v[30:31], v[32:33], v[142:143] op_sel_hi:[1,0]
	v_cvt_pk_bf16_f32 v26, v26, v27
	v_mul_f32_e32 v32, 0xbfb8aa3b, v30
	v_mul_f32_e32 v33, 0xbfb8aa3b, v31
	v_exp_f32_e32 v32, v32
	v_exp_f32_e32 v33, v33
	v_add_f32_e32 v32, 1.0, v32
	v_add_f32_e32 v33, 1.0, v33
	v_rcp_f32_e32 v32, v32
	v_rcp_f32_e32 v33, v33
	s_nop 0
	v_pk_mul_f32 v[30:31], v[30:31], v[32:33]
	s_nop 0
	v_pk_mul_f32 v[28:29], v[28:29], v[30:31]
	s_nop 0
	v_cvt_pk_bf16_f32 v27, v28, v29
	v_mul_f32_e32 v28, 0xbfb8aa3b, v22
	v_mul_f32_e32 v29, 0xbfb8aa3b, v23
	v_exp_f32_e32 v28, v28
	v_exp_f32_e32 v29, v29
	v_add_f32_e32 v28, 1.0, v28
	v_add_f32_e32 v29, 1.0, v29
	v_rcp_f32_e32 v28, v28
	v_rcp_f32_e32 v29, v29
	s_nop 0
	v_pk_mul_f32 v[22:23], v[22:23], v[28:29]
	s_nop 0
	v_pk_mul_f32 v[18:19], v[18:19], v[22:23]
	v_pk_mul_f32 v[22:23], v[24:25], v[142:143] op_sel_hi:[1,0]
	v_cvt_pk_bf16_f32 v28, v18, v19
	v_mul_f32_e32 v24, 0xbfb8aa3b, v22
	v_mul_f32_e32 v25, 0xbfb8aa3b, v23
	v_exp_f32_e32 v24, v24
	v_exp_f32_e32 v25, v25
	v_add_u32_e32 v18, 0xa0, v118
	v_mad_i64_i32 v[18:19], s[22:23], v18, s66, v[114:115]
	v_add_f32_e32 v24, 1.0, v24
	v_add_f32_e32 v25, 1.0, v25
	v_rcp_f32_e32 v24, v24
	v_rcp_f32_e32 v25, v25
	v_lshl_add_u64 v[18:19], v[18:19], 0, v[116:117]
	v_pk_mul_f32 v[22:23], v[22:23], v[24:25]
	s_nop 0
	v_pk_mul_f32 v[20:21], v[20:21], v[22:23]
	s_nop 0
	v_cvt_pk_bf16_f32 v29, v20, v21
	global_store_dwordx4 v[18:19], v[26:29], off
	v_mul_f32_e32 v18, 0xbfb8aa3b, v14
	v_mul_f32_e32 v19, 0xbfb8aa3b, v15
	v_exp_f32_e32 v18, v18
	v_exp_f32_e32 v19, v19
	v_add_f32_e32 v18, 1.0, v18
	v_add_f32_e32 v19, 1.0, v19
	v_rcp_f32_e32 v18, v18
	v_rcp_f32_e32 v19, v19
	s_nop 0
	v_pk_mul_f32 v[14:15], v[14:15], v[18:19]
	s_nop 0
	v_pk_mul_f32 v[10:11], v[10:11], v[14:15]
	v_pk_mul_f32 v[14:15], v[16:17], v[140:141] op_sel_hi:[1,0]
	v_cvt_pk_bf16_f32 v10, v10, v11
	v_mul_f32_e32 v16, 0xbfb8aa3b, v14
	v_mul_f32_e32 v17, 0xbfb8aa3b, v15
	v_exp_f32_e32 v16, v16
	v_exp_f32_e32 v17, v17
	v_add_f32_e32 v16, 1.0, v16
	v_add_f32_e32 v17, 1.0, v17
	v_rcp_f32_e32 v16, v16
	v_rcp_f32_e32 v17, v17
	s_nop 0
	v_pk_mul_f32 v[14:15], v[14:15], v[16:17]
	s_nop 0
	v_pk_mul_f32 v[12:13], v[12:13], v[14:15]
	s_nop 0
	v_cvt_pk_bf16_f32 v11, v12, v13
	v_mul_f32_e32 v12, 0xbfb8aa3b, v6
	v_mul_f32_e32 v13, 0xbfb8aa3b, v7
	v_exp_f32_e32 v12, v12
	v_exp_f32_e32 v13, v13
	v_add_f32_e32 v12, 1.0, v12
	v_add_f32_e32 v13, 1.0, v13
	v_rcp_f32_e32 v12, v12
	v_rcp_f32_e32 v13, v13
	s_nop 0
	v_pk_mul_f32 v[6:7], v[6:7], v[12:13]
	s_nop 0
	v_pk_mul_f32 v[2:3], v[2:3], v[6:7]
	v_pk_mul_f32 v[6:7], v[8:9], v[140:141] op_sel_hi:[1,0]
	v_cvt_pk_bf16_f32 v12, v2, v3
	v_mul_f32_e32 v8, 0xbfb8aa3b, v6
	v_mul_f32_e32 v9, 0xbfb8aa3b, v7
	v_exp_f32_e32 v8, v8
	v_exp_f32_e32 v9, v9
	v_add_u32_e32 v2, 0xb0, v118
	v_mad_i64_i32 v[2:3], s[22:23], v2, s66, v[114:115]
	v_add_f32_e32 v8, 1.0, v8
	v_add_f32_e32 v9, 1.0, v9
	v_rcp_f32_e32 v8, v8
	v_rcp_f32_e32 v9, v9
	v_lshl_add_u64 v[2:3], v[2:3], 0, v[116:117]
	s_mov_b64 s[22:23], -1
	v_pk_mul_f32 v[6:7], v[6:7], v[8:9]
	s_nop 0
	v_pk_mul_f32 v[4:5], v[4:5], v[6:7]
	s_nop 0
	v_cvt_pk_bf16_f32 v13, v4, v5
	global_store_dwordx4 v[2:3], v[10:13], off
	s_cbranch_vccnz .LBB0_1229
	s_andn2_b64 vcc, exec, s[2:3]
	s_cbranch_vccnz .LBB0_1228
	s_barrier
	s_branch .LBB0_1228
